# speedup vs baseline: 1.0725x; 1.0100x over previous
.LBB0_154:
	v_ashrrev_i32_e32 v20, 5, v12
	v_mul_u32_u24_e32 v12, 0x104, v4
	v_lshlrev_b32_e32 v13, 2, v20
	v_add3_u32 v21, 0, v12, v13
	ds_read2_b32 v[12:13], v21 offset1:16
	ds_read2_b32 v[14:15], v21 offset0:65 offset1:81
	s_ashr_i32 vcc_hi, vcc_lo, 31
	s_add_i32 s6, s6, s30
	s_lshl_b64 s[8:9], vcc, 1
	s_add_u32 s8, s14, s8
	s_waitcnt lgkmcnt(1)
	v_mov_b32_e32 v18, v12
	s_waitcnt lgkmcnt(0)
	v_mov_b32_e32 v19, v14
	v_add_u32_e32 v20, s6, v20
	s_addc_u32 s9, s15, s9
	v_lshlrev_b32_e32 v4, 1, v4
	s_waitcnt vmcnt(0)
	v_pk_mul_f32 v[18:19], v[10:11], v[18:19]
	v_ashrrev_i32_e32 v12, 31, v20
	v_lshl_add_u64 v[16:17], s[8:9], 0, v[4:5]
	v_cvt_pk_bf16_f32 v4, v18, v19
	v_mul_lo_u32 v12, s92, v12
	v_mul_lo_u32 v14, s93, v20
	v_mad_u64_u32 v[18:19], s[8:9], s92, v20, 0
	v_add3_u32 v19, v19, v12, v14
	v_lshl_add_u64 v[18:19], v[18:19], 1, v[16:17]
	v_mov_b32_e32 v14, v13
	global_store_dword v[18:19], v4, off sc0 sc1
	v_pk_mul_f32 v[12:13], v[10:11], v[14:15]
	ds_read2_b32 v[14:15], v21 offset0:32 offset1:48
	ds_read2_b32 v[18:19], v21 offset0:97 offset1:113
	v_cvt_pk_bf16_f32 v4, v12, v13
	v_add_u32_e32 v12, 16, v20
	v_ashrrev_i32_e32 v13, 31, v12
	v_mul_lo_u32 v22, s92, v13
	v_mul_lo_u32 v23, s93, v12
	v_mad_u64_u32 v[12:13], s[8:9], s92, v12, 0
	v_add3_u32 v13, v13, v22, v23
	v_lshl_add_u64 v[12:13], v[12:13], 1, v[16:17]
	global_store_dword v[12:13], v4, off sc0 sc1
	s_waitcnt lgkmcnt(1)
	v_mov_b32_e32 v12, v14
	s_waitcnt lgkmcnt(0)
	v_mov_b32_e32 v13, v18
	v_pk_mul_f32 v[12:13], v[10:11], v[12:13]
	s_nop 0
	v_cvt_pk_bf16_f32 v4, v12, v13
	v_add_u32_e32 v12, 32, v20
	v_ashrrev_i32_e32 v13, 31, v12
	v_mul_lo_u32 v14, s92, v13
	v_mul_lo_u32 v18, s93, v12
	v_mad_u64_u32 v[12:13], s[8:9], s92, v12, 0
	v_add3_u32 v13, v13, v14, v18
	v_mov_b32_e32 v18, v15
	v_lshl_add_u64 v[12:13], v[12:13], 1, v[16:17]
	v_pk_mul_f32 v[10:11], v[10:11], v[18:19]
	global_store_dword v[12:13], v4, off sc0 sc1
	v_cvt_pk_bf16_f32 v4, v10, v11
	v_add_u32_e32 v10, 48, v20
	v_ashrrev_i32_e32 v11, 31, v10
	v_mul_lo_u32 v12, s92, v11
	v_mul_lo_u32 v13, s93, v10
	v_mad_u64_u32 v[10:11], s[8:9], s92, v10, 0
	v_add3_u32 v11, v11, v12, v13
	v_lshl_add_u64 v[10:11], v[10:11], 1, v[16:17]
	global_store_dword v[10:11], v4, off sc0 sc1

.LBB0_156:
	s_cmpk_gt_i32 s3, 0xb7f
	s_mov_b64 s[8:9], -1
	s_cbranch_scc0 .LBB0_162
	s_cmpk_gt_u32 s3, 0x137f
	s_cbranch_scc0 .LBB0_174
	s_cmpk_gt_u32 s3, 0x1b7f
	s_cbranch_scc0 .LBB0_171
	s_cmpk_gt_u32 s3, 0x1b97
	s_cbranch_scc0 .LBB0_168
	s_add_i32 s30, s3, 0xffffe468
	s_lshl_b32 s12, s30, 6
	v_or_b32_e32 v4, s12, v31
	s_lshl_b64 s[8:9], s[30:31], 2
	v_lshlrev_b64 v[10:11], 2, v[4:5]
	s_add_u32 s8, s66, s8
	s_addc_u32 s9, s67, s9
	v_lshl_add_u64 v[12:13], s[62:63], 0, v[10:11]
	global_load_dword v20, v5, s[8:9]
	v_lshl_add_u64 v[10:11], s[64:65], 0, v[10:11]
	global_load_dword v12, v[12:13], off
	s_mov_b32 s92, 0x652b82fe
	global_load_dword v10, v[10:11], off
	s_mov_b32 s90, 0xeb1c432d
	s_mov_b32 s93, 0x3ff71547
	s_mov_b32 s91, 0xbf1a36e2
	s_mov_b32 s8, 0xfca7ab0c
	s_mov_b32 s94, 0x3b39803f
	s_mov_b32 s9, 0x3e928af3
	s_mov_b32 s95, 0xbc7abc9e
	s_mov_b32 s22, 0x6a5dcb37
	v_mov_b64_e32 v[14:15], s[8:9]
	s_mov_b32 s23, 0x3e5ade15
	v_readlane_b32 s6, v252, 16
	v_readlane_b32 s7, v252, 17
	s_mov_b32 s24, 0x14761f6e
	s_mov_b32 s25, 0x3f2a01a0
	s_mov_b32 s6, 0x1852b7b0
	s_mov_b32 s7, 0x3f56c16c
	s_mov_b32 s68, 0x11122322
	s_mov_b32 s69, 0x3f811111
	s_mov_b32 s20, 11
	s_mov_b32 s21, 0x3fe00000
	s_mov_b32 s8, 0x44800000
	s_mov_b32 s9, 0xc4866000
	s_mov_b32 s4, 0x54442d18
	s_mov_b32 s5, 0x401921fb
	s_mov_b32 s16, s4
	s_mov_b32 s10, 0
	s_mov_b32 s11, 0x40900000
	s_mov_b32 s14, 0
	s_mov_b32 s15, 0xc090cc00
	s_waitcnt vmcnt(2)
	v_cvt_f64_f32_e32 v[16:17], v20
	v_mul_f64 v[18:19], v[16:17], s[92:93]
	s_waitcnt vmcnt(1)
	v_cvt_f64_f32_e32 v[12:13], v12
	v_cmp_nlt_f64_e32 vcc, s[90:91], v[12:13]
	s_mov_b32 s90, 0xfefa39ef
	v_rndne_f64_e32 v[18:19], v[18:19]
	s_mov_b32 s91, 0xbfe62e42
	v_fmac_f64_e32 v[16:17], s[90:91], v[18:19]
	v_fmac_f64_e32 v[16:17], s[94:95], v[18:19]
	v_cvt_i32_f64_e32 v21, v[18:19]
	v_fma_f64 v[18:19], s[22:23], v[16:17], v[14:15]
	v_fma_f64 v[18:19], v[16:17], v[18:19], s[96:97]
	v_fma_f64 v[18:19], v[16:17], v[18:19], s[34:35]
	v_fma_f64 v[18:19], v[16:17], v[18:19], s[24:25]
	v_fma_f64 v[18:19], v[16:17], v[18:19], s[6:7]
	v_fma_f64 v[18:19], v[16:17], v[18:19], s[68:69]
	v_fma_f64 v[18:19], v[16:17], v[18:19], s[28:29]
	v_fma_f64 v[18:19], v[16:17], v[18:19], s[26:27]
	v_fma_f64 v[18:19], v[16:17], v[18:19], s[20:21]
	v_fma_f64 v[18:19], v[16:17], v[18:19], 1.0
	v_fma_f64 v[16:17], v[16:17], v[18:19], 1.0
	v_cndmask_b32_e32 v13, v38, v13, vcc
	v_cndmask_b32_e32 v12, v39, v12, vcc
	v_ldexp_f64 v[16:17], v[16:17], v21
	v_cmp_nlt_f32_e32 vcc, s8, v20
	v_cmp_ngt_f32_e64 s[8:9], s9, v20
	s_waitcnt vmcnt(0)
	v_cvt_f64_f32_e32 v[10:11], v10
	v_cndmask_b32_e32 v17, v40, v17, vcc
	s_and_b64 vcc, s[8:9], vcc
	v_cndmask_b32_e64 v17, 0, v17, s[8:9]
	v_cndmask_b32_e32 v16, 0, v16, vcc
	v_mul_f64 v[18:19], v[12:13], v[16:17]
	v_mul_f64 v[16:17], v[16:17], v[10:11]
	v_mul_f64 v[20:21], v[18:19], s[92:93]
	v_div_scale_f64 v[22:23], s[8:9], s[4:5], s[4:5], v[16:17]
	v_rcp_f64_e32 v[46:47], v[22:23]
	v_rndne_f64_e32 v[20:21], v[20:21]
	v_fma_f64 v[48:49], s[90:91], v[20:21], v[18:19]
	v_fmac_f64_e32 v[48:49], s[94:95], v[20:21]
	v_fmac_f64_e32 v[14:15], s[22:23], v[48:49]
	v_cvt_i32_f64_e32 v50, v[20:21]
	v_fma_f64 v[20:21], -v[22:23], v[46:47], 1.0
	v_fma_f64 v[14:15], v[48:49], v[14:15], s[96:97]
	v_fmac_f64_e32 v[46:47], v[46:47], v[20:21]
	v_fma_f64 v[14:15], v[48:49], v[14:15], s[34:35]
	v_fma_f64 v[20:21], -v[22:23], v[46:47], 1.0
	v_fma_f64 v[14:15], v[48:49], v[14:15], s[24:25]
	v_div_scale_f64 v[24:25], vcc, v[16:17], s[4:5], v[16:17]
	v_fmac_f64_e32 v[46:47], v[46:47], v[20:21]
	v_fma_f64 v[14:15], v[48:49], v[14:15], s[6:7]
	v_mul_f64 v[20:21], v[24:25], v[46:47]
	v_fma_f64 v[14:15], v[48:49], v[14:15], s[68:69]
	v_fma_f64 v[22:23], -v[22:23], v[20:21], v[24:25]
	v_fma_f64 v[14:15], v[48:49], v[14:15], s[28:29]
	v_div_fmas_f64 v[20:21], v[22:23], v[46:47], v[20:21]
	v_fma_f64 v[14:15], v[48:49], v[14:15], s[26:27]
	v_fma_f64 v[14:15], v[48:49], v[14:15], s[20:21]
	v_div_fixup_f64 v[20:21], v[20:21], s[4:5], v[16:17]
	v_fma_f64 v[14:15], v[48:49], v[14:15], 1.0
	v_rndne_f64_e32 v[20:21], v[20:21]
	v_fma_f64 v[14:15], v[48:49], v[14:15], 1.0
	v_fmac_f64_e32 v[16:17], s[16:17], v[20:21]
	v_ldexp_f64 v[14:15], v[14:15], v50
	v_ldexp_f64 v[20:21], v[16:17], -3
	v_cmp_nlt_f64_e32 vcc, s[10:11], v[18:19]
	s_mov_b32 s4, 0
	v_mul_f64 v[16:17], v[20:21], v[20:21]
	v_cndmask_b32_e32 v15, v40, v15, vcc
	v_cmp_ngt_f64_e64 s[8:9], s[14:15], v[18:19]
	s_mov_b32 s5, 0xc0180000
	s_mov_b32 s6, 0
	v_cndmask_b32_e64 v15, 0, v15, s[8:9]
	s_and_b64 vcc, s[8:9], vcc
	v_div_scale_f64 v[18:19], s[8:9], s[4:5], s[4:5], v[16:17]
	s_mov_b32 s7, 0xc0340000
	s_mov_b32 s20, 0
	v_div_scale_f64 v[24:25], s[8:9], s[6:7], s[6:7], v[16:17]
	s_mov_b32 s21, 0xc0450000
	v_rcp_f64_e32 v[54:55], v[18:19]
	v_div_scale_f64 v[48:49], s[10:11], s[20:21], s[20:21], v[16:17]
	v_rcp_f64_e32 v[56:57], v[24:25]
	s_mov_b32 s22, 0
	v_rcp_f64_e32 v[58:59], v[48:49]
	s_mov_b32 s23, 0xc0520000
	v_div_scale_f64 v[52:53], s[14:15], s[22:23], s[22:23], v[16:17]
	v_fma_f64 v[62:63], -v[18:19], v[54:55], 1.0
	v_rcp_f64_e32 v[60:61], v[52:53]
	v_fma_f64 v[64:65], -v[24:25], v[56:57], 1.0
	v_fmac_f64_e32 v[54:55], v[54:55], v[62:63]
	v_fma_f64 v[66:67], -v[48:49], v[58:59], 1.0
	v_fmac_f64_e32 v[56:57], v[56:57], v[64:65]
	v_fma_f64 v[62:63], -v[18:19], v[54:55], 1.0
	v_cndmask_b32_e32 v14, 0, v14, vcc
	v_div_scale_f64 v[22:23], vcc, v[16:17], s[4:5], v[16:17]
	v_fmac_f64_e32 v[58:59], v[58:59], v[66:67]
	v_fma_f64 v[64:65], -v[24:25], v[56:57], 1.0
	v_fmac_f64_e32 v[54:55], v[54:55], v[62:63]
	v_div_scale_f64 v[46:47], s[8:9], v[16:17], s[6:7], v[16:17]
	v_fma_f64 v[66:67], -v[48:49], v[58:59], 1.0
	v_fmac_f64_e32 v[56:57], v[56:57], v[64:65]
	v_mul_f64 v[62:63], v[22:23], v[54:55]
	v_div_scale_f64 v[50:51], s[10:11], v[16:17], s[20:21], v[16:17]
	v_fma_f64 v[68:69], -v[52:53], v[60:61], 1.0
	v_fmac_f64_e32 v[58:59], v[58:59], v[66:67]
	v_mul_f64 v[64:65], v[46:47], v[56:57]
	v_fma_f64 v[18:19], -v[18:19], v[62:63], v[22:23]
	v_fmac_f64_e32 v[60:61], v[60:61], v[68:69]
	v_mul_f64 v[66:67], v[50:51], v[58:59]
	v_fma_f64 v[22:23], -v[24:25], v[64:65], v[46:47]
	v_div_fmas_f64 v[18:19], v[18:19], v[54:55], v[62:63]
	s_mov_b64 vcc, s[8:9]
	v_fma_f64 v[68:69], -v[52:53], v[60:61], 1.0
	v_fma_f64 v[24:25], -v[48:49], v[66:67], v[50:51]
	v_div_fixup_f64 v[18:19], v[18:19], s[4:5], v[16:17]
	v_div_fmas_f64 v[22:23], v[22:23], v[56:57], v[64:65]
	s_mov_b64 vcc, s[10:11]
	s_mov_b32 s4, 0
	v_fmac_f64_e32 v[60:61], v[60:61], v[68:69]
	v_div_fmas_f64 v[24:25], v[24:25], v[58:59], v[66:67]
	v_div_scale_f64 v[46:47], vcc, v[16:17], s[22:23], v[16:17]
	s_mov_b32 s5, 0xc05b8000
	v_mul_f64 v[48:49], v[46:47], v[60:61]
	v_div_scale_f64 v[50:51], s[8:9], s[4:5], s[4:5], v[16:17]
	v_fma_f64 v[46:47], -v[52:53], v[48:49], v[46:47]
	v_rcp_f64_e32 v[52:53], v[50:51]
	v_div_fmas_f64 v[46:47], v[46:47], v[60:61], v[48:49]
	v_div_fixup_f64 v[22:23], v[22:23], s[6:7], v[16:17]
	s_mov_b32 s6, 0
	v_fma_f64 v[48:49], -v[50:51], v[52:53], 1.0
	v_fmac_f64_e32 v[52:53], v[52:53], v[48:49]
	v_fma_f64 v[48:49], -v[50:51], v[52:53], 1.0
	v_fmac_f64_e32 v[52:53], v[52:53], v[48:49]
	v_div_scale_f64 v[48:49], vcc, v[16:17], s[4:5], v[16:17]
	v_mul_f64 v[54:55], v[48:49], v[52:53]
	s_mov_b32 s7, 0xc0638000
	v_fma_f64 v[48:49], -v[50:51], v[54:55], v[48:49]
	v_div_scale_f64 v[50:51], s[8:9], s[6:7], s[6:7], v[16:17]
	v_rcp_f64_e32 v[56:57], v[50:51]
	v_div_fmas_f64 v[48:49], v[48:49], v[52:53], v[54:55]
	v_div_fixup_f64 v[48:49], v[48:49], s[4:5], v[16:17]
	v_div_fixup_f64 v[46:47], v[46:47], s[22:23], v[16:17]
	v_fma_f64 v[52:53], -v[50:51], v[56:57], 1.0
	v_fmac_f64_e32 v[56:57], v[56:57], v[52:53]
	v_fma_f64 v[52:53], -v[50:51], v[56:57], 1.0
	v_fmac_f64_e32 v[56:57], v[56:57], v[52:53]
	v_div_scale_f64 v[52:53], vcc, v[16:17], s[6:7], v[16:17]
	v_mul_f64 v[54:55], v[52:53], v[56:57]
	v_fma_f64 v[50:51], -v[50:51], v[54:55], v[52:53]
	v_div_fixup_f64 v[24:25], v[24:25], s[20:21], v[16:17]
	s_nop 0
	v_div_fmas_f64 v[50:51], v[50:51], v[56:57], v[54:55]
	v_div_fixup_f64 v[50:51], v[50:51], s[6:7], v[16:17]
	v_add_f64 v[50:51], v[50:51], 1.0
	v_fma_f64 v[48:49], v[48:49], v[50:51], 1.0
	v_fma_f64 v[46:47], v[46:47], v[48:49], 1.0
	s_mov_b32 s4, 0
	v_fma_f64 v[24:25], v[24:25], v[46:47], 1.0
	s_mov_b32 s5, 0xc0280000
	v_fma_f64 v[22:23], v[22:23], v[24:25], 1.0
	v_div_scale_f64 v[24:25], s[8:9], s[4:5], s[4:5], v[16:17]
	v_rcp_f64_e32 v[46:47], v[24:25]
	v_fma_f64 v[18:19], v[18:19], v[22:23], 1.0
	s_mov_b32 s6, 0
	s_mov_b32 s7, 0xc03e0000
	v_fma_f64 v[22:23], -v[24:25], v[46:47], 1.0
	v_fmac_f64_e32 v[46:47], v[46:47], v[22:23]
	v_fma_f64 v[22:23], -v[24:25], v[46:47], 1.0
	v_fmac_f64_e32 v[46:47], v[46:47], v[22:23]
	v_div_scale_f64 v[22:23], vcc, v[16:17], s[4:5], v[16:17]
	v_mul_f64 v[48:49], v[22:23], v[46:47]
	v_fma_f64 v[22:23], -v[24:25], v[48:49], v[22:23]
	v_div_scale_f64 v[24:25], s[8:9], s[6:7], s[6:7], v[16:17]
	v_rcp_f64_e32 v[50:51], v[24:25]
	v_div_fmas_f64 v[22:23], v[22:23], v[46:47], v[48:49]
	v_div_fixup_f64 v[22:23], v[22:23], s[4:5], v[16:17]
	s_mov_b32 s4, 0
	v_fma_f64 v[46:47], -v[24:25], v[50:51], 1.0
	v_fmac_f64_e32 v[50:51], v[50:51], v[46:47]
	v_fma_f64 v[46:47], -v[24:25], v[50:51], 1.0
	v_fmac_f64_e32 v[50:51], v[50:51], v[46:47]
	v_div_scale_f64 v[46:47], vcc, v[16:17], s[6:7], v[16:17]
	v_mul_f64 v[48:49], v[46:47], v[50:51]
	s_mov_b32 s5, 0xc04c0000
	v_fma_f64 v[24:25], -v[24:25], v[48:49], v[46:47]
	v_div_scale_f64 v[46:47], s[8:9], s[4:5], s[4:5], v[16:17]
	v_rcp_f64_e32 v[52:53], v[46:47]
	v_div_fmas_f64 v[24:25], v[24:25], v[50:51], v[48:49]
	v_div_fixup_f64 v[24:25], v[24:25], s[6:7], v[16:17]
	s_mov_b32 s6, 0
	v_fma_f64 v[48:49], -v[46:47], v[52:53], 1.0
	v_fmac_f64_e32 v[52:53], v[52:53], v[48:49]
	v_fma_f64 v[48:49], -v[46:47], v[52:53], 1.0
	v_fmac_f64_e32 v[52:53], v[52:53], v[48:49]
	v_div_scale_f64 v[48:49], vcc, v[16:17], s[4:5], v[16:17]
	v_mul_f64 v[50:51], v[48:49], v[52:53]
	s_mov_b32 s7, 0xc0568000
	v_fma_f64 v[46:47], -v[46:47], v[50:51], v[48:49]
	v_div_scale_f64 v[48:49], s[8:9], s[6:7], s[6:7], v[16:17]
	v_rcp_f64_e32 v[54:55], v[48:49]
	v_div_fmas_f64 v[46:47], v[46:47], v[52:53], v[50:51]
	v_div_fixup_f64 v[46:47], v[46:47], s[4:5], v[16:17]
	s_mov_b32 s4, 0
	v_fma_f64 v[50:51], -v[48:49], v[54:55], 1.0
	v_fmac_f64_e32 v[54:55], v[54:55], v[50:51]
	v_fma_f64 v[50:51], -v[48:49], v[54:55], 1.0
	v_fmac_f64_e32 v[54:55], v[54:55], v[50:51]
	v_div_scale_f64 v[50:51], vcc, v[16:17], s[6:7], v[16:17]
	v_mul_f64 v[52:53], v[50:51], v[54:55]
	s_mov_b32 s5, 0xc0608000
	v_fma_f64 v[48:49], -v[48:49], v[52:53], v[50:51]
	v_div_scale_f64 v[50:51], s[8:9], s[4:5], s[4:5], v[16:17]
	v_rcp_f64_e32 v[56:57], v[50:51]
	v_div_fmas_f64 v[48:49], v[48:49], v[54:55], v[52:53]
	v_div_fixup_f64 v[48:49], v[48:49], s[6:7], v[16:17]
	s_mov_b32 s6, 0
	v_fma_f64 v[52:53], -v[50:51], v[56:57], 1.0
	v_fmac_f64_e32 v[56:57], v[56:57], v[52:53]
	v_fma_f64 v[52:53], -v[50:51], v[56:57], 1.0
	v_fmac_f64_e32 v[56:57], v[56:57], v[52:53]
	v_div_scale_f64 v[52:53], vcc, v[16:17], s[4:5], v[16:17]
	v_mul_f64 v[54:55], v[52:53], v[56:57]
	s_mov_b32 s7, 0xc066c000
	v_fma_f64 v[50:51], -v[50:51], v[54:55], v[52:53]
	v_div_scale_f64 v[52:53], s[8:9], s[6:7], s[6:7], v[16:17]
	v_rcp_f64_e32 v[58:59], v[52:53]
	v_div_fmas_f64 v[50:51], v[50:51], v[56:57], v[54:55]
	v_mul_f64 v[18:19], v[20:21], v[18:19]
	v_mul_f64 v[20:21], v[16:17], -0.5
	v_fma_f64 v[54:55], -v[52:53], v[58:59], 1.0
	v_fmac_f64_e32 v[58:59], v[58:59], v[54:55]
	v_fma_f64 v[54:55], -v[52:53], v[58:59], 1.0
	v_fmac_f64_e32 v[58:59], v[58:59], v[54:55]
	v_div_scale_f64 v[54:55], vcc, v[16:17], s[6:7], v[16:17]
	v_mul_f64 v[56:57], v[54:55], v[58:59]
	v_fma_f64 v[52:53], -v[52:53], v[56:57], v[54:55]
	v_div_fixup_f64 v[50:51], v[50:51], s[4:5], v[16:17]
	s_nop 0
	v_div_fmas_f64 v[52:53], v[52:53], v[58:59], v[56:57]
	v_div_fixup_f64 v[16:17], v[52:53], s[6:7], v[16:17]
	v_add_f64 v[16:17], v[16:17], 1.0
	v_fma_f64 v[16:17], v[50:51], v[16:17], 1.0
	v_fma_f64 v[16:17], v[48:49], v[16:17], 1.0
	v_fma_f64 v[16:17], v[46:47], v[16:17], 1.0
	v_fma_f64 v[16:17], v[24:25], v[16:17], 1.0
	v_fma_f64 v[16:17], v[22:23], v[16:17], 1.0
	v_fma_f64 v[16:17], v[20:21], v[16:17], 1.0
	v_add_f64 v[20:21], v[18:19], v[18:19]
	v_mul_f64 v[20:21], v[16:17], v[20:21]
	v_mul_f64 v[18:19], v[18:19], v[18:19]
	v_fma_f64 v[16:17], v[16:17], v[16:17], -v[18:19]
	v_add_f64 v[18:19], v[20:21], v[20:21]
	v_mul_f64 v[18:19], v[16:17], v[18:19]
	v_mul_f64 v[20:21], v[20:21], v[20:21]
	v_fma_f64 v[16:17], v[16:17], v[16:17], -v[20:21]
	v_add_f64 v[20:21], v[18:19], v[18:19]
	v_mul_f64 v[18:19], v[18:19], v[18:19]
	v_mul_f64 v[20:21], v[16:17], v[20:21]
	v_fma_f64 v[16:17], v[16:17], v[16:17], -v[18:19]
	v_readlane_b32 s4, v252, 48
	v_mul_f64 v[16:17], v[14:15], v[16:17]
	v_mul_f64 v[14:15], v[14:15], v[20:21]
	v_readlane_b32 s5, v252, 49
	s_and_saveexec_b64 s[8:9], s[4:5]
	s_cbranch_execz .LBB0_167
	v_readlane_b32 s10, v252, 24
	v_readlane_b32 s11, v252, 25
	v_cvt_f32_f64_e32 v20, v[16:17]
	s_mov_b32 s6, 9
	v_lshl_add_u64 v[18:19], v[4:5], 2, s[10:11]
	global_store_dword v[18:19], v20, off sc0 sc1
	v_add_u32_e32 v18, s12, v26
	v_mov_b32_e32 v19, v5
	v_cvt_f32_f64_e32 v20, v[14:15]
	v_lshl_add_u64 v[18:19], v[18:19], 2, s[10:11]
	global_store_dword v[18:19], v20, off sc0 sc1
	v_add_u32_e32 v18, s12, v27
	v_mov_b32_e32 v19, v5
	v_lshl_add_u64 v[20:21], v[18:19], 2, s[10:11]
	v_add_u32_e32 v18, s12, v28
	v_lshl_add_u64 v[22:23], v[18:19], 2, s[10:11]
	v_mov_b64_e32 v[18:19], v[14:15]
	v_mov_b64_e32 v[24:25], v[16:17]
	s_branch .LBB0_164

.LBB0_164:
	v_mul_f64 v[46:47], v[18:19], v[18:19]
	v_mov_b64_e32 v[48:49], v[24:25]
	v_fma_f64 v[24:25], v[48:49], v[48:49], -v[46:47]
	v_add_f64 v[46:47], v[48:49], v[48:49]
	s_cmp_lg_u32 s6, 6
	v_mul_f64 v[18:19], v[18:19], v[46:47]
	s_cbranch_scc1 .LBB0_163
	v_cvt_f32_f64_e32 v46, v[24:25]
	v_cvt_f32_f64_e32 v47, v[18:19]
	global_store_dword v[20:21], v46, off sc0 sc1
	global_store_dword v[22:23], v47, off sc0 sc1
	s_branch .LBB0_163
.LBB0_166:
	v_readlane_b32 s10, v252, 24
	v_add_u32_e32 v20, s12, v29
	v_mov_b32_e32 v21, v5
	v_readlane_b32 s11, v252, 25
	v_cvt_f32_f64_e32 v22, v[24:25]
	s_nop 0
	v_lshl_add_u64 v[20:21], v[20:21], 2, s[10:11]
	global_store_dword v[20:21], v22, off sc0 sc1
	v_cvt_f32_f64_e32 v20, v[18:19]
	v_add_u32_e32 v18, s12, v30
	v_mov_b32_e32 v19, v5
	v_lshl_add_u64 v[18:19], v[18:19], 2, s[10:11]
	global_store_dword v[18:19], v20, off sc0 sc1
.LBB0_167:
	s_or_b64 exec, exec, s[8:9]
	v_lshlrev_b32_e32 v4, 4, v4
	v_add_u32_e32 v18, v4, v32
	v_ashrrev_i32_e32 v19, 31, v18
	v_readlane_b32 s68, v252, 0
	v_lshlrev_b64 v[18:19], 2, v[18:19]
	v_readlane_b32 s69, v252, 1
	v_readlane_b32 s70, v252, 2
	v_readlane_b32 s71, v252, 3
	v_lshl_add_u64 v[20:21], s[68:69], 0, v[18:19]
	global_load_dword v56, v[20:21], off
	v_lshl_add_u64 v[18:19], s[70:71], 0, v[18:19]
	global_load_dword v57, v[18:19], off
	s_lshl_b32 s6, s30, 4
	v_add_u32_e32 v59, s6, v32
	v_add_u32_e32 v22, v4, v37
	v_lshl_or_b32 v24, v59, 6, v31
	v_ashrrev_i32_e32 v23, 31, v22
	v_ashrrev_i32_e32 v25, 31, v24
	v_readlane_b32 s72, v252, 4
	v_readlane_b32 s73, v252, 5
	v_lshlrev_b64 v[22:23], 2, v[22:23]
	v_lshlrev_b64 v[24:25], 2, v[24:25]
	v_readlane_b32 s74, v252, 6
	v_readlane_b32 s75, v252, 7
	v_lshl_add_u64 v[46:47], s[68:69], 0, v[22:23]
	v_lshl_add_u64 v[48:49], s[72:73], 0, v[24:25]
	v_lshl_add_u64 v[24:25], s[74:75], 0, v[24:25]
	global_load_dword v4, v[48:49], off
	global_load_dword v60, v[24:25], off
	v_lshl_add_u64 v[22:23], s[70:71], 0, v[22:23]
	global_load_dword v61, v[46:47], off
	global_load_dword v62, v[22:23], off
	v_add_f64 v[16:17], v[16:17], -1.0
	v_mul_f64 v[18:19], v[12:13], v[12:13]
	v_mul_f64 v[20:21], v[12:13], v[16:17]
	v_mul_f64 v[16:17], v[16:17], v[10:11]
	v_add_u32_e32 v66, s6, v37
	v_fmac_f64_e32 v[18:19], v[10:11], v[10:11]
	v_fmac_f64_e32 v[20:21], v[14:15], v[10:11]
	v_fma_f64 v[10:11], v[12:13], v[14:15], -v[16:17]
	v_lshl_or_b32 v14, v66, 6, v31
	v_ashrrev_i32_e32 v15, 31, v14
	v_lshlrev_b64 v[14:15], 2, v[14:15]
	v_lshl_add_u64 v[54:55], s[72:73], 0, v[14:15]
	v_lshl_add_u64 v[14:15], s[74:75], 0, v[14:15]
	global_load_dword v67, v[54:55], off
	global_load_dword v68, v[14:15], off
	v_div_scale_f64 v[16:17], s[8:9], v[18:19], v[18:19], v[20:21]
	v_div_scale_f64 v[46:47], s[8:9], v[18:19], v[18:19], v[10:11]
	v_rcp_f64_e32 v[50:51], v[16:17]
	v_rcp_f64_e32 v[52:53], v[46:47]
	v_div_scale_f64 v[24:25], vcc, v[20:21], v[18:19], v[20:21]
	v_fma_f64 v[14:15], -v[16:17], v[50:51], 1.0
	v_fma_f64 v[54:55], -v[46:47], v[52:53], 1.0
	v_fmac_f64_e32 v[50:51], v[50:51], v[14:15]
	v_fmac_f64_e32 v[52:53], v[52:53], v[54:55]
	v_fma_f64 v[14:15], -v[16:17], v[50:51], 1.0
	v_fma_f64 v[54:55], -v[46:47], v[52:53], 1.0
	v_fmac_f64_e32 v[50:51], v[50:51], v[14:15]
	v_div_scale_f64 v[48:49], s[8:9], v[10:11], v[18:19], v[10:11]
	v_fmac_f64_e32 v[52:53], v[52:53], v[54:55]
	v_mul_f64 v[14:15], v[24:25], v[50:51]
	v_mul_f64 v[54:55], v[48:49], v[52:53]
	v_fma_f64 v[16:17], -v[16:17], v[14:15], v[24:25]
	v_fma_f64 v[24:25], -v[46:47], v[54:55], v[48:49]
	v_div_fmas_f64 v[14:15], v[16:17], v[50:51], v[14:15]
	s_mov_b64 vcc, s[8:9]
	v_div_fmas_f64 v[16:17], v[24:25], v[52:53], v[54:55]
	v_div_fixup_f64 v[14:15], v[14:15], v[18:19], v[20:21]
	v_div_fixup_f64 v[10:11], v[16:17], v[18:19], v[10:11]
	v_lshl_or_b32 v58, s30, 12, v34
	v_or_b32_e32 v63, 16, v58
	v_add_u32_e32 v12, v63, v32
	v_ashrrev_i32_e32 v13, 31, v12
	v_or_b32_e32 v64, 32, v58
	v_lshl_add_u64 v[12:13], v[12:13], 1, s[18:19]
	v_or_b32_e32 v65, 48, v58
	v_add_u32_e32 v22, v58, v32
	v_readlane_b32 s8, v252, 26
	v_ashrrev_i32_e32 v23, 31, v22
	v_readlane_b32 s9, v252, 27
	v_lshl_add_u64 v[22:23], v[22:23], 1, s[18:19]
	v_readlane_b32 s20, v252, 54
	v_readlane_b32 s22, v252, 52
	v_readlane_b32 s24, v252, 50
	v_readlane_b32 s76, v252, 8
	v_readlane_b32 s77, v252, 9
	v_readlane_b32 s78, v252, 10
	s_waitcnt vmcnt(7)
	v_cvt_f64_f32_e32 v[16:17], v56
	v_readlane_b32 s79, v252, 11
	s_waitcnt vmcnt(6)
	v_cvt_f64_f32_e32 v[18:19], v57
	v_mul_f64 v[20:21], v[10:11], v[18:19]
	v_mul_f64 v[18:19], v[14:15], v[18:19]
	v_fma_f64 v[20:21], v[14:15], v[16:17], -v[20:21]
	v_fmac_f64_e32 v[18:19], v[10:11], v[16:17]
	v_cvt_f32_f64_e32 v16, v[20:21]
	v_cvt_f32_f64_e32 v17, v[18:19]
	v_cvt_pk_bf16_f32 v18, v16, s0
	v_lshlrev_b32_e32 v20, 16, v18
	v_sub_f32_e32 v16, v16, v20
	v_cvt_pk_bf16_f32 v16, v16, s0
	global_store_short v[12:13], v16, off sc0 sc1
	v_add_u32_e32 v12, v64, v32
	v_ashrrev_i32_e32 v13, 31, v12
	v_cvt_pk_bf16_f32 v19, v17, s0
	v_lshl_add_u64 v[12:13], v[12:13], 1, s[18:19]
	v_lshlrev_b32_e32 v21, 16, v19
	global_store_short v[12:13], v19, off sc0 sc1
	v_add_u32_e32 v12, v65, v32
	v_sub_f32_e32 v17, v17, v21
	v_ashrrev_i32_e32 v13, 31, v12
	v_cvt_pk_bf16_f32 v17, v17, s0
	v_lshl_add_u64 v[12:13], v[12:13], 1, s[18:19]
	global_store_short v[12:13], v17, off sc0 sc1
	v_lshl_or_b32 v12, v59, 7, v33
	v_ashrrev_i32_e32 v13, 31, v12
	v_lshl_add_u64 v[12:13], v[12:13], 1, s[8:9]
	s_waitcnt vmcnt(7)
	v_cvt_pk_bf16_f32 v4, v4, -v60
	s_waitcnt vmcnt(5)
	v_cvt_f64_f32_e32 v[16:17], v62
	global_store_short v[22:23], v18, off sc0 sc1
	global_store_dword v[12:13], v4, off sc0 sc1
	v_cvt_f64_f32_e32 v[12:13], v61
	v_mul_f64 v[18:19], v[10:11], v[16:17]
	v_fma_f64 v[18:19], v[14:15], v[12:13], -v[18:19]
	v_mul_f64 v[14:15], v[14:15], v[16:17]
	v_cvt_f32_f64_e32 v4, v[18:19]
	v_fmac_f64_e32 v[14:15], v[10:11], v[12:13]
	v_cvt_f32_f64_e32 v10, v[14:15]
	v_cvt_pk_bf16_f32 v12, v4, s0
	v_lshlrev_b32_e32 v11, 16, v12
	v_cvt_pk_bf16_f32 v13, v10, s0
	v_sub_f32_e32 v4, v4, v11
	v_lshlrev_b32_e32 v11, 16, v13
	v_sub_f32_e32 v10, v10, v11
	v_cvt_pk_bf16_f32 v14, v10, s0
	v_add_u32_e32 v10, v58, v37
	v_ashrrev_i32_e32 v11, 31, v10
	v_lshl_add_u64 v[10:11], v[10:11], 1, s[18:19]
	global_store_short v[10:11], v12, off sc0 sc1
	v_add_u32_e32 v10, v63, v37
	v_ashrrev_i32_e32 v11, 31, v10
	v_cvt_pk_bf16_f32 v4, v4, s0
	v_lshl_add_u64 v[10:11], v[10:11], 1, s[18:19]
	global_store_short v[10:11], v4, off sc0 sc1
	v_add_u32_e32 v10, v64, v37
	v_ashrrev_i32_e32 v11, 31, v10
	v_lshl_add_u64 v[10:11], v[10:11], 1, s[18:19]
	global_store_short v[10:11], v13, off sc0 sc1
	v_add_u32_e32 v10, v65, v37
	v_ashrrev_i32_e32 v11, 31, v10
	v_lshl_add_u64 v[10:11], v[10:11], 1, s[18:19]
	global_store_short v[10:11], v14, off sc0 sc1
	v_lshl_or_b32 v10, v66, 7, v33
	v_ashrrev_i32_e32 v11, 31, v10
	v_lshl_add_u64 v[10:11], v[10:11], 1, s[8:9]
	s_waitcnt vmcnt(9)
	v_cvt_pk_bf16_f32 v4, v67, -v68
	v_readlane_b32 s80, v252, 12
	v_readlane_b32 s81, v252, 13
	v_readlane_b32 s82, v252, 14
	v_readlane_b32 s83, v252, 15
	global_store_dword v[10:11], v4, off sc0 sc1
	s_mov_b64 s[8:9], 0
	v_readlane_b32 s21, v252, 55
	v_readlane_b32 s23, v252, 53
	v_readlane_b32 s25, v252, 51
.LBB0_168:
	s_and_b64 vcc, exec, s[8:9]
	s_cbranch_vccz .LBB0_170
	v_lshl_add_u32 v10, s3, 11, v35
	v_readlane_b32 s8, v252, 28
	v_ashrrev_i32_e32 v11, 31, v10
	v_readlane_b32 s9, v252, 29
	s_nop 1
	v_lshl_add_u64 v[10:11], v[10:11], 2, s[8:9]
	global_store_dwordx4 v[10:11], v[42:45], off sc0 sc1

.Lnsb_do:
	s_add_i32 s30, s3, 0xffffec80
	s_lshl_b64 s[8:9], s[30:31], 12
	v_lshl_add_u64 v[18:19], s[8:9], 0, v[2:3]
	v_lshl_add_u64 v[14:15], v[18:19], 2, s[54:55]
	global_load_dwordx4 v[10:13], v[14:15], off
	s_nop 0
	global_load_dwordx4 v[14:17], v[14:15], off offset:16
	s_waitcnt vmcnt(1)
	v_cvt_pk_bf16_f32 v10, v10, v11
	v_cvt_pk_bf16_f32 v11, v12, v13
	s_waitcnt vmcnt(0)
	v_cvt_pk_bf16_f32 v12, v14, v15
	v_cvt_pk_bf16_f32 v13, v16, v17
	v_lshl_add_u64 v[14:15], v[18:19], 1, s[20:21]
	global_store_dwordx4 v[14:15], v[10:13], off sc0 sc1

.LBB0_174:
	s_andn2_b64 vcc, exec, s[8:9]
	s_cbranch_vccnz .LBB0_178
	s_lshl_b32 s6, s3, 11
	s_and_b32 s6, s6, 0x3800
	s_add_i32 s6, s3, s6
	s_addk_i32 s6, 0xf480
	s_and_b32 s6, s6, -8
	v_add_u32_e32 v10, s6, v36
	v_ashrrev_i32_e32 v11, 31, v10
	v_lshlrev_b64 v[12:13], 12, v[10:11]
	v_lshl_add_u64 v[24:25], v[8:9], 0, v[12:13]
	global_load_dwordx4 v[12:15], v[24:25], off
	global_load_dwordx4 v[70:73], v[24:25], off offset:1024
	global_load_dwordx4 v[74:77], v[24:25], off offset:2048
	global_load_dwordx4 v[78:81], v[24:25], off offset:3072
	v_lshlrev_b64 v[16:17], 11, v[10:11]
	v_lshl_add_u64 v[50:51], v[6:7], 0, v[16:17]
	v_and_b32_e32 v4, 64, v41
	v_add_u32_e32 v4, 64, v4
	v_readlane_b32 s4, v252, 20
	v_readlane_b32 s5, v252, 21
	s_waitcnt vmcnt(3)
	v_cvt_pk_bf16_f32 v16, v12, v13
	v_cvt_pk_bf16_f32 v17, v14, v15
	global_store_dwordx2 v[50:51], v[16:17], off sc0 sc1
	v_pk_mul_f32 v[12:13], v[12:13], v[12:13]
	v_pk_mul_f32 v[14:15], v[14:15], v[14:15]
	v_add_f32_e32 v12, v12, v13
	v_add_f32_e32 v12, v12, v14
	s_waitcnt vmcnt(3)
	v_cvt_pk_bf16_f32 v20, v70, v71
	v_cvt_pk_bf16_f32 v21, v72, v73
	global_store_dwordx2 v[50:51], v[20:21], off offset:512 sc0 sc1
	s_waitcnt vmcnt(3)
	v_cvt_pk_bf16_f32 v46, v74, v75
	v_cvt_pk_bf16_f32 v47, v76, v77
	global_store_dwordx2 v[50:51], v[46:47], off offset:1024 sc0 sc1
	v_add_f32_e32 v25, v12, v15
	v_pk_mul_f32 v[12:13], v[70:71], v[70:71]
	v_pk_mul_f32 v[14:15], v[72:73], v[72:73]
	v_add_f32_e32 v12, v12, v13
	v_add_f32_e32 v12, v12, v14
	v_add_f32_e32 v12, v12, v15
	v_add_f32_e32 v82, v25, v12
	v_pk_mul_f32 v[12:13], v[74:75], v[74:75]
	v_pk_mul_f32 v[14:15], v[76:77], v[76:77]
	v_add_f32_e32 v12, v12, v13
	v_add_f32_e32 v12, v12, v14
	v_add_f32_e32 v12, v12, v15
	v_add_f32_e32 v82, v82, v12
	v_xor_b32_e32 v24, 32, v41
	v_cmp_lt_i32_e32 vcc, v24, v4
	s_waitcnt vmcnt(3)
	v_pk_mul_f32 v[12:13], v[78:79], v[78:79]
	v_pk_mul_f32 v[14:15], v[80:81], v[80:81]
	v_add_f32_e32 v12, v12, v13
	v_add_f32_e32 v12, v12, v14
	v_cndmask_b32_e32 v24, v41, v24, vcc
	v_add_f32_e32 v12, v12, v15
	v_lshlrev_b32_e32 v24, 2, v24
	v_add_f32_e32 v12, v82, v12
	ds_bpermute_b32 v13, v24, v12
	v_xor_b32_e32 v14, 16, v41
	v_cmp_lt_i32_e32 vcc, v14, v4
	v_cvt_pk_bf16_f32 v15, v80, v81
	s_waitcnt lgkmcnt(0)
	v_add_f32_e32 v12, v12, v13
	v_cndmask_b32_e32 v14, v41, v14, vcc
	v_lshlrev_b32_e32 v14, 2, v14
	ds_bpermute_b32 v13, v14, v12
	v_xor_b32_e32 v14, 8, v41
	v_cmp_lt_i32_e32 vcc, v14, v4
	s_waitcnt lgkmcnt(0)
	v_add_f32_e32 v12, v12, v13
	v_cndmask_b32_e32 v14, v41, v14, vcc
	v_lshlrev_b32_e32 v14, 2, v14
	ds_bpermute_b32 v13, v14, v12
	v_xor_b32_e32 v14, 4, v41
	v_cmp_lt_i32_e32 vcc, v14, v4
	s_waitcnt lgkmcnt(0)
	v_add_f32_e32 v12, v12, v13
	v_cndmask_b32_e32 v14, v41, v14, vcc
	v_lshlrev_b32_e32 v14, 2, v14
	ds_bpermute_b32 v13, v14, v12
	v_xor_b32_e32 v14, 2, v41
	v_cmp_lt_i32_e32 vcc, v14, v4
	s_waitcnt lgkmcnt(0)
	v_add_f32_e32 v12, v12, v13
	v_cndmask_b32_e32 v14, v41, v14, vcc
	v_lshlrev_b32_e32 v14, 2, v14
	ds_bpermute_b32 v13, v14, v12
	v_xor_b32_e32 v14, 1, v41
	v_cmp_lt_i32_e32 vcc, v14, v4
	s_waitcnt lgkmcnt(0)
	v_add_f32_e32 v4, v12, v13
	v_cndmask_b32_e32 v14, v41, v14, vcc
	v_lshlrev_b32_e32 v12, 2, v14
	ds_bpermute_b32 v12, v12, v4
	v_cvt_pk_bf16_f32 v14, v78, v79
	global_store_dwordx2 v[50:51], v[14:15], off offset:1536 sc0 sc1
	s_and_saveexec_b64 s[8:9], s[4:5]
	s_cbranch_execz .LBB0_177
	s_waitcnt lgkmcnt(0)
	v_add_f32_e32 v4, v4, v12
	v_lshl_add_u64 v[10:11], v[10:11], 2, s[22:23]
	global_store_dword v[10:11], v4, off sc0 sc1

.Lnsb_go:
	s_and_b32 s99, s98, 63
	s_lshr_b32 s30, s98, 6
	s_lshl_b32 s30, s30, 8
	s_add_u32 s30, s30, s99
	s_addk_i32 s30, 0x218
	s_lshl_b64 s[8:9], s[30:31], 12
	v_lshl_add_u64 v[18:19], s[8:9], 0, v[2:3]
	v_lshl_add_u64 v[14:15], v[18:19], 2, s[54:55]
	global_load_dwordx4 v[10:13], v[14:15], off
	global_load_dwordx4 v[84:87], v[14:15], off offset:16
	s_add_u32 s98, s98, 0xc0
	s_and_b32 s99, s98, 63
	s_lshr_b32 s30, s98, 6
	s_lshl_b32 s30, s30, 8
	s_add_u32 s30, s30, s99
	s_addk_i32 s30, 0x218
	s_lshl_b64 s[8:9], s[30:31], 12
	v_lshl_add_u64 v[98:99], s[8:9], 0, v[2:3]
	v_lshl_add_u64 v[88:89], v[98:99], 2, s[54:55]
	global_load_dwordx4 v[90:93], v[88:89], off
	global_load_dwordx4 v[94:97], v[88:89], off offset:16
	s_waitcnt vmcnt(3)
	v_cvt_pk_bf16_f32 v10, v10, v11
	v_cvt_pk_bf16_f32 v11, v12, v13
	s_waitcnt vmcnt(2)
	v_cvt_pk_bf16_f32 v12, v84, v85
	v_cvt_pk_bf16_f32 v13, v86, v87
	v_lshl_add_u64 v[14:15], v[18:19], 1, s[20:21]
	global_store_dwordx4 v[14:15], v[10:13], off sc0 sc1
	s_waitcnt vmcnt(2)
	v_cvt_pk_bf16_f32 v90, v90, v91
	v_cvt_pk_bf16_f32 v91, v92, v93
	s_waitcnt vmcnt(1)
	v_cvt_pk_bf16_f32 v92, v94, v95
	v_cvt_pk_bf16_f32 v93, v96, v97
	v_lshl_add_u64 v[88:89], v[98:99], 1, s[20:21]
	global_store_dwordx4 v[88:89], v[90:93], off sc0 sc1

.LBB0_226:
	s_or_b64 exec, exec, s[8:9]
	s_waitcnt vmcnt(0)
	buffer_inv sc1
	s_waitcnt vmcnt(0)
	s_load_dwordx2 s[6:7], s[92:93], 0xd8
	s_load_dword s12, s[92:93], 0xe0
	s_mov_b64 s[8:9], exec
	v_mbcnt_lo_u32_b32 v1, s8, 0
	v_mbcnt_hi_u32_b32 v1, s9, v1
	v_cmp_eq_u32_e32 vcc, 0, v1
	s_and_saveexec_b64 s[10:11], vcc
	s_cbranch_execz .LBB0_228
	s_bcnt1_i32_b64 s8, s[8:9]
	v_mov_b32_e32 v2, 0
	v_mov_b32_e32 v3, s8
	global_atomic_add v2, v2, v3, s[88:89] sc0

.LBB0_242:
	s_or_b64 exec, exec, s[6:7]
	v_mov_b32_e32 v1, 0x2b00000
	s_waitcnt vmcnt(0)
	buffer_inv sc1
	global_load_dword v2, v1, s[86:87] offset:1024 sc1
	global_load_dword v4, v1, s[86:87] offset:1280 sc1
	global_load_dword v6, v1, s[86:87] offset:1536 sc1
	global_load_dword v7, v1, s[86:87] offset:1792 sc1
	global_load_dword v8, v1, s[86:87] offset:2048 sc1
	global_load_dword v9, v1, s[86:87] offset:2304 sc1
	global_load_dword v10, v1, s[86:87] offset:2560 sc1
	global_load_dword v11, v1, s[86:87] offset:2816 sc1
	global_load_dword v12, v1, s[86:87] offset:3072 sc1
	global_load_dword v13, v1, s[86:87] offset:3328 sc1
	global_load_dword v14, v1, s[86:87] offset:3584 sc1
	global_load_dword v15, v1, s[86:87] offset:3840 sc1
	v_mov_b32_e32 v1, 0x2b01000
	global_load_dword v16, v1, s[86:87] sc1
	global_load_dword v17, v1, s[86:87] offset:256 sc1
	global_load_dword v18, v1, s[86:87] offset:512 sc1
	global_load_dword v19, v1, s[86:87] offset:768 sc1
	v_mov_b32_e32 v5, 0
	global_load_dword v3, v5, s[4:5] offset:1024 sc1
	global_load_dwordx4 v[20:23], v5, s[88:89] offset:768 sc1
	global_load_dwordx4 v[24:27], v5, s[88:89] offset:784 sc1
	s_load_dword s100, s[92:93], 0xd8
	s_waitcnt vmcnt(16)
	v_cmp_ne_u32_e32 vcc, 0, v2
	s_nop 1
	v_cndmask_b32_e64 v1, 0, 1, vcc
	s_waitcnt vmcnt(14)
	v_cmp_ne_u32_e32 vcc, 0, v6
	s_nop 1
	v_cndmask_b32_e64 v2, 0, 1, vcc
	s_waitcnt vmcnt(12)
	v_cmp_ne_u32_e32 vcc, 0, v8
	s_nop 1
	v_cndmask_b32_e64 v6, 0, 1, vcc
	s_waitcnt vmcnt(10)
	v_cmp_ne_u32_e32 vcc, 0, v10
	s_nop 1
	v_cndmask_b32_e64 v8, 0, 1, vcc
	s_waitcnt vmcnt(8)
	v_cmp_ne_u32_e32 vcc, 0, v12
	s_nop 1
	v_cndmask_b32_e64 v10, 0, 1, vcc
	s_waitcnt vmcnt(6)
	v_cmp_ne_u32_e32 vcc, 0, v14
	s_nop 1
	v_cndmask_b32_e64 v12, 0, 1, vcc
	s_waitcnt vmcnt(4)
	v_cmp_ne_u32_e32 vcc, 0, v16
	s_nop 1
	v_cndmask_b32_e64 v14, 0, 1, vcc
	s_waitcnt vmcnt(2)
	v_cmp_ne_u32_e32 vcc, 0, v18
	s_nop 1
	v_cndmask_b32_e64 v16, 0, 1, vcc
	v_cmp_ne_u32_e32 vcc, 0, v4
	s_nop 1
	v_addc_co_u32_e32 v1, vcc, 0, v1, vcc
	v_cmp_ne_u32_e32 vcc, 0, v7
	s_nop 1
	v_addc_co_u32_e32 v1, vcc, v1, v2, vcc
	v_cmp_ne_u32_e32 vcc, 0, v9
	v_mov_b32_e32 v2, s3
	s_nop 0
	v_addc_co_u32_e32 v1, vcc, v1, v6, vcc
	v_cmp_ne_u32_e32 vcc, 0, v11
	s_nop 1
	v_addc_co_u32_e32 v1, vcc, v1, v8, vcc
	v_cmp_ne_u32_e32 vcc, 0, v13
	s_nop 1
	v_addc_co_u32_e32 v1, vcc, v1, v10, vcc
	v_cmp_ne_u32_e32 vcc, 0, v15
	s_nop 1
	v_addc_co_u32_e32 v1, vcc, v1, v12, vcc
	v_cmp_ne_u32_e32 vcc, 0, v17
	s_nop 1
	v_addc_co_u32_e32 v1, vcc, v1, v14, vcc
	s_waitcnt vmcnt(1)
	v_cmp_ne_u32_e32 vcc, 0, v19
	s_nop 1
	v_addc_co_u32_e32 v4, vcc, v1, v16, vcc
	s_waitcnt vmcnt(0)
	v_add_u32_e32 v28, -1, v20
	v_and_b32_e32 v28, v28, v20
	v_cmp_eq_u32_e32 vcc, 0, v20
	s_nop 1
	v_cndmask_b32_e64 v29, 0, 1, vcc
	v_or_b32_e32 v28, v28, v29
	v_mov_b32_e32 v30, v28
	v_add_u32_e32 v28, -1, v21
	v_and_b32_e32 v28, v28, v21
	v_cmp_eq_u32_e32 vcc, 0, v21
	s_nop 1
	v_cndmask_b32_e64 v29, 0, 1, vcc
	v_or_b32_e32 v28, v28, v29
	v_or_b32_e32 v30, v30, v28
	v_add_u32_e32 v28, -1, v22
	v_and_b32_e32 v28, v28, v22
	v_cmp_eq_u32_e32 vcc, 0, v22
	s_nop 1
	v_cndmask_b32_e64 v29, 0, 1, vcc
	v_or_b32_e32 v28, v28, v29
	v_or_b32_e32 v30, v30, v28
	v_add_u32_e32 v28, -1, v23
	v_and_b32_e32 v28, v28, v23
	v_cmp_eq_u32_e32 vcc, 0, v23
	s_nop 1
	v_cndmask_b32_e64 v29, 0, 1, vcc
	v_or_b32_e32 v28, v28, v29
	v_or_b32_e32 v30, v30, v28
	v_add_u32_e32 v28, -1, v24
	v_and_b32_e32 v28, v28, v24
	v_cmp_eq_u32_e32 vcc, 0, v24
	s_nop 1
	v_cndmask_b32_e64 v29, 0, 1, vcc
	v_or_b32_e32 v28, v28, v29
	v_or_b32_e32 v30, v30, v28
	v_add_u32_e32 v28, -1, v25
	v_and_b32_e32 v28, v28, v25
	v_cmp_eq_u32_e32 vcc, 0, v25
	s_nop 1
	v_cndmask_b32_e64 v29, 0, 1, vcc
	v_or_b32_e32 v28, v28, v29
	v_or_b32_e32 v30, v30, v28
	v_add_u32_e32 v28, -1, v26
	v_and_b32_e32 v28, v28, v26
	v_cmp_eq_u32_e32 vcc, 0, v26
	s_nop 1
	v_cndmask_b32_e64 v29, 0, 1, vcc
	v_or_b32_e32 v28, v28, v29
	v_or_b32_e32 v30, v30, v28
	v_add_u32_e32 v28, -1, v27
	v_and_b32_e32 v28, v28, v27
	v_cmp_eq_u32_e32 vcc, 0, v27
	s_nop 1
	v_cndmask_b32_e64 v29, 0, 1, vcc
	v_or_b32_e32 v28, v28, v29
	v_or_b32_e32 v30, v30, v28
	s_waitcnt lgkmcnt(0)
	s_nop 0
	v_readfirstlane_b32 s101, v30
	s_and_b32 s98, s100, 7
	s_lshr_b32 s100, s100, 3
	s_nop 1
	s_or_b32 s101, s101, s98
	ds_write_b128 v5, v[2:5]
